# mixer-B fast path as its own loop: 4-stage LDS ring, per-wave progress words with one-iteration-lag barrier instead of a per-tile barrier; packed row sums; chain decay matrix straight-line
# speedup vs baseline: 1.0807x; 1.0090x over previous
; #define MFMA(a, b, c) __builtin_amdgcn_mfma_f32_32x32x16_bf16((a), (b), (c), 0, 0, 0)
; DI int crow(int e, int h) { return (e & 3) + 8 * (e >> 2) + 4 * h; }
; DI void mlstm_chain(const Params& p, int layer, char* smem, VBC& vc, int chain) {
;     ...
;                 f32x16 sx[2];
; #pragma unroll
;                 for (int si = 0; si < 2; ++si)
; #pragma unroll
;                     for (int e = 0; e < 16; ++e) sx[si][e] = 0.f;
; #pragma unroll
;                 for (int ks = 0; ks < 4; ++ks)
; #pragma unroll
;                     for (int si = 0; si < 2; ++si) sx[si] = MFMA(ld8(sK + (si * 32 + r) * AST + ks * 16 + h * 8), qfr[ks], sx[si]);
; #pragma unroll
;                 for (int si = 0; si < 2; ++si) {
; #pragma unroll
;                     for (int e = 0; e < 16; ++e) {
;                         const int sidx = si * 32 + crow(e, h);
;                         const bool valid = dir ? (sidx >= t) : (sidx <= t);
;                         const float dm = valid ? __expf(bt + s_a[sidx] - mtt) : 0.f;
;                         const float pv = sx[si][e] * dm; sx[si][e] = pv; dsum += pv;
.LBB0_833:
	ds_read_b128 v[34:37], v107 offset:9216
	ds_read_b128 v[38:41], v124
	v_mov_b32_e32 v129, 0
	s_waitcnt lgkmcnt(0)
	v_mfma_f32_32x32x16_bf16 v[50:65], v[34:37], v[38:41], 0
	ds_read_b128 v[34:37], v107 offset:13824
	ds_read_b128 v[130:133], v107 offset:9248
	ds_read_b128 v[134:137], v124 offset:32
	s_waitcnt lgkmcnt(0)
	v_mfma_f32_32x32x16_bf16 v[50:65], v[130:133], v[134:137], v[50:65]
	ds_read_b128 v[130:133], v107 offset:13856
	v_mfma_f32_32x32x16_bf16 v[34:49], v[34:37], v[38:41], 0
	s_waitcnt lgkmcnt(0)
	v_mfma_f32_32x32x16_bf16 v[34:49], v[130:133], v[134:137], v[34:49]
	ds_read_b128 v[130:133], v107 offset:9280
	ds_read_b128 v[134:137], v124 offset:64
	s_waitcnt lgkmcnt(0)
	v_mfma_f32_32x32x16_bf16 v[50:65], v[130:133], v[134:137], v[50:65]
	ds_read_b128 v[130:133], v107 offset:13888
	s_waitcnt lgkmcnt(0)
	v_mfma_f32_32x32x16_bf16 v[34:49], v[130:133], v[134:137], v[34:49]
	ds_read_b128 v[130:133], v107 offset:9312
	ds_read_b128 v[134:137], v124 offset:96
	ds_read_b128 v[138:141], v107 offset:13920
	ds_read_b32 v108, v123 offset:38144
	ds_read2st64_b32 v[110:111], v123 offset0:146 offset1:148
	s_waitcnt lgkmcnt(3)
	v_mfma_f32_32x32x16_bf16 v[50:65], v[130:133], v[134:137], v[50:65]
	v_mov_b32_e32 v130, 0
	s_waitcnt lgkmcnt(2)
	v_mfma_f32_32x32x16_bf16 v[34:49], v[138:141], v[134:137], v[34:49]
	ds_read_b128 v[162:165], v104 offset:37632
	ds_read_b128 v[166:169], v104 offset:37664
	ds_read_b128 v[170:173], v104 offset:37696
	ds_read_b128 v[174:177], v104 offset:37728
	ds_read_b128 v[178:181], v104 offset:37760
	ds_read_b128 v[182:185], v104 offset:37792
	ds_read_b128 v[186:189], v104 offset:37824
	ds_read_b128 v[190:193], v104 offset:37856
	s_waitcnt lgkmcnt(0)
	v_add_f32_e32 v130, v110, v162
	v_add_f32_e32 v131, v110, v163
	v_add_f32_e32 v129, v110, v164
	v_add_f32_e32 v133, v110, v165
	v_add_f32_e32 v132, v110, v166
	v_add_f32_e32 v135, v110, v167
	v_add_f32_e32 v134, v110, v168
	v_add_f32_e32 v137, v110, v169
	v_add_f32_e32 v136, v110, v170
	v_add_f32_e32 v139, v110, v171
	v_add_f32_e32 v138, v110, v172
	v_add_f32_e32 v141, v110, v173
	v_add_f32_e32 v140, v110, v174
	v_add_f32_e32 v143, v110, v175
	v_add_f32_e32 v142, v110, v176
	v_add_f32_e32 v145, v110, v177
	v_add_f32_e32 v144, v110, v178
	v_add_f32_e32 v147, v110, v179
	v_add_f32_e32 v146, v110, v180
	v_add_f32_e32 v149, v110, v181
	v_add_f32_e32 v148, v110, v182
	v_add_f32_e32 v151, v110, v183
	v_add_f32_e32 v150, v110, v184
	v_add_f32_e32 v153, v110, v185
	v_add_f32_e32 v152, v110, v186
	v_add_f32_e32 v155, v110, v187
	v_add_f32_e32 v154, v110, v188
	v_add_f32_e32 v157, v110, v189
	v_add_f32_e32 v156, v110, v190
	v_add_f32_e32 v159, v110, v191
	v_add_f32_e32 v158, v110, v192
	v_add_f32_e32 v160, v110, v193
	v_sub_f32_e32 v130, v130, v111
	v_sub_f32_e32 v131, v131, v111
	v_sub_f32_e32 v129, v129, v111
	v_sub_f32_e32 v133, v133, v111
	v_sub_f32_e32 v132, v132, v111
	v_sub_f32_e32 v135, v135, v111
	v_sub_f32_e32 v134, v134, v111
	v_sub_f32_e32 v137, v137, v111
	v_sub_f32_e32 v136, v136, v111
	v_sub_f32_e32 v139, v139, v111
	v_sub_f32_e32 v138, v138, v111
	v_sub_f32_e32 v141, v141, v111
	v_sub_f32_e32 v140, v140, v111
	v_sub_f32_e32 v143, v143, v111
	v_sub_f32_e32 v142, v142, v111
	v_sub_f32_e32 v145, v145, v111
	v_sub_f32_e32 v144, v144, v111
	v_sub_f32_e32 v147, v147, v111
	v_sub_f32_e32 v146, v146, v111
	v_sub_f32_e32 v149, v149, v111
	v_sub_f32_e32 v148, v148, v111
	v_sub_f32_e32 v151, v151, v111
	v_sub_f32_e32 v150, v150, v111
	v_sub_f32_e32 v153, v153, v111
	v_sub_f32_e32 v152, v152, v111
	v_sub_f32_e32 v155, v155, v111
	v_sub_f32_e32 v154, v154, v111
	v_sub_f32_e32 v157, v157, v111
	v_sub_f32_e32 v156, v156, v111
	v_sub_f32_e32 v159, v159, v111
	v_sub_f32_e32 v158, v158, v111
	v_sub_f32_e32 v160, v160, v111
	v_mul_f32_e32 v130, 0x3fb8aa3b, v130
	v_mul_f32_e32 v131, 0x3fb8aa3b, v131
	v_mul_f32_e32 v129, 0x3fb8aa3b, v129
	v_mul_f32_e32 v133, 0x3fb8aa3b, v133
	v_mul_f32_e32 v132, 0x3fb8aa3b, v132
	v_mul_f32_e32 v135, 0x3fb8aa3b, v135
	v_mul_f32_e32 v134, 0x3fb8aa3b, v134
	v_mul_f32_e32 v137, 0x3fb8aa3b, v137
	v_mul_f32_e32 v136, 0x3fb8aa3b, v136
	v_mul_f32_e32 v139, 0x3fb8aa3b, v139
	v_mul_f32_e32 v138, 0x3fb8aa3b, v138
	v_mul_f32_e32 v141, 0x3fb8aa3b, v141
	v_mul_f32_e32 v140, 0x3fb8aa3b, v140
	v_mul_f32_e32 v143, 0x3fb8aa3b, v143
	v_mul_f32_e32 v142, 0x3fb8aa3b, v142
	v_mul_f32_e32 v145, 0x3fb8aa3b, v145
	v_mul_f32_e32 v144, 0x3fb8aa3b, v144
	v_mul_f32_e32 v147, 0x3fb8aa3b, v147
	v_mul_f32_e32 v146, 0x3fb8aa3b, v146
	v_mul_f32_e32 v149, 0x3fb8aa3b, v149
	v_mul_f32_e32 v148, 0x3fb8aa3b, v148
	v_mul_f32_e32 v151, 0x3fb8aa3b, v151
	v_mul_f32_e32 v150, 0x3fb8aa3b, v150
	v_mul_f32_e32 v153, 0x3fb8aa3b, v153
	v_mul_f32_e32 v152, 0x3fb8aa3b, v152
	v_mul_f32_e32 v155, 0x3fb8aa3b, v155
	v_mul_f32_e32 v154, 0x3fb8aa3b, v154
	v_mul_f32_e32 v157, 0x3fb8aa3b, v157
	v_mul_f32_e32 v156, 0x3fb8aa3b, v156
	v_mul_f32_e32 v159, 0x3fb8aa3b, v159
	v_mul_f32_e32 v158, 0x3fb8aa3b, v158
	v_mul_f32_e32 v160, 0x3fb8aa3b, v160
	v_exp_f32_e32 v130, v130
	v_exp_f32_e32 v131, v131
	v_exp_f32_e32 v129, v129
	v_exp_f32_e32 v133, v133
	v_exp_f32_e32 v132, v132
	v_exp_f32_e32 v135, v135
	v_exp_f32_e32 v134, v134
	v_exp_f32_e32 v137, v137
	v_exp_f32_e32 v136, v136
	v_exp_f32_e32 v139, v139
	v_exp_f32_e32 v138, v138
	v_exp_f32_e32 v141, v141
	v_exp_f32_e32 v140, v140
	v_exp_f32_e32 v143, v143
	v_exp_f32_e32 v142, v142
	v_exp_f32_e32 v145, v145
	v_exp_f32_e32 v144, v144
	v_exp_f32_e32 v147, v147
	v_exp_f32_e32 v146, v146
	v_exp_f32_e32 v149, v149
	v_exp_f32_e32 v148, v148
	v_exp_f32_e32 v151, v151
	v_exp_f32_e32 v150, v150
	v_exp_f32_e32 v153, v153
	v_exp_f32_e32 v152, v152
	v_exp_f32_e32 v155, v155
; #define MFMA(a, b, c) __builtin_amdgcn_mfma_f32_32x32x16_bf16((a), (b), (c), 0, 0, 0)
; DI int crow(int e, int h) { return (e & 3) + 8 * (e >> 2) + 4 * h; }
; DI void mlstm_chain(const Params& p, int layer, char* smem, VBC& vc, int chain) {
;     ...
;                 for (int si = 0; si < 2; ++si) {
; #pragma unroll
;                     for (int e = 0; e < 16; ++e) {
;                         const int sidx = si * 32 + crow(e, h);
;                         const bool valid = dir ? (sidx >= t) : (sidx <= t);
;                         const float dm = valid ? __expf(bt + s_a[sidx] - mtt) : 0.f;
;                         const float pv = sx[si][e] * dm; sx[si][e] = pv; dsum += pv;
;                     }
;                     pf[si][0] = pack8(sx[si], 0); pf[si][1] = pack8(sx[si], 1);
;                 }
;             }
;             dsum += __shfl_xor(dsum, 32);
;             f32x16 Z;
; #pragma unroll
;             for (int e = 0; e < 16; ++e) Z[e] = 0.f;
; #pragma unroll
;             for (int dt = 0; dt < 2; ++dt)
; #pragma unroll
;                 for (int sp = 0; sp < 2; ++sp) {
;                     const u16* qp = sQ + t * AST + dt * 32 + sp * 16 + 4 * h;
;                     Z = MFMA(pack8(Cst[dt], sp), ld4x2(qp, qp + 8), Z);
	v_exp_f32_e32 v154, v154
	v_exp_f32_e32 v157, v157
	v_exp_f32_e32 v156, v156
	v_exp_f32_e32 v159, v159
	v_exp_f32_e32 v158, v158
	v_exp_f32_e32 v160, v160
	v_cndmask_b32_e64 v130, 0, v130, s[42:43]
	v_cndmask_b32_e64 v131, 0, v131, s[58:59]
	v_cndmask_b32_e64 v129, 0, v129, s[72:73]
	v_cndmask_b32_e64 v133, 0, v133, s[74:75]
	v_cndmask_b32_e64 v132, 0, v132, s[76:77]
	v_cndmask_b32_e64 v135, 0, v135, s[78:79]
	v_cndmask_b32_e64 v134, 0, v134, s[80:81]
	v_cndmask_b32_e64 v137, 0, v137, s[82:83]
	v_cndmask_b32_e64 v136, 0, v136, s[84:85]
	v_cndmask_b32_e64 v139, 0, v139, s[86:87]
	v_cndmask_b32_e64 v138, 0, v138, s[88:89]
	v_cndmask_b32_e64 v141, 0, v141, s[90:91]
	v_cndmask_b32_e64 v140, 0, v140, s[22:23]
	v_cndmask_b32_e64 v143, 0, v143, s[96:97]
	v_cndmask_b32_e64 v150, 0, v150, s[2:3]
	v_cndmask_b32_e64 v153, 0, v153, s[4:5]
	v_cndmask_b32_e64 v152, 0, v152, s[6:7]
	v_cndmask_b32_e64 v155, 0, v155, s[8:9]
	v_cndmask_b32_e64 v154, 0, v154, s[10:11]
	v_cndmask_b32_e64 v157, 0, v157, s[12:13]
	v_cndmask_b32_e64 v156, 0, v156, s[14:15]
	v_cndmask_b32_e64 v159, 0, v159, s[16:17]
	v_cndmask_b32_e64 v158, 0, v158, s[18:19]
	v_cndmask_b32_e64 v160, 0, v160, s[20:21]
	v_readlane_b32 s24, v250, 9
	v_readlane_b32 s25, v250, 10
	s_nop 1
	v_cndmask_b32_e64 v142, 0, v142, s[24:25]
	v_readlane_b32 s24, v250, 11
	v_readlane_b32 s25, v250, 12
	s_nop 1
	v_cndmask_b32_e64 v145, 0, v145, s[24:25]
	v_readlane_b32 s24, v250, 13
	v_readlane_b32 s25, v250, 14
	s_nop 1
	v_cndmask_b32_e64 v144, 0, v144, s[24:25]
	v_readlane_b32 s24, v250, 15
	v_readlane_b32 s25, v250, 16
	s_nop 1
	v_cndmask_b32_e64 v147, 0, v147, s[24:25]
	v_readlane_b32 s24, v250, 17
	v_readlane_b32 s25, v250, 18
	s_nop 1
	v_cndmask_b32_e64 v146, 0, v146, s[24:25]
	v_readlane_b32 s24, v250, 19
	v_readlane_b32 s25, v250, 20
	s_nop 1
	v_cndmask_b32_e64 v149, 0, v149, s[24:25]
	v_readlane_b32 s24, v250, 21
	v_readlane_b32 s25, v250, 22
	s_nop 1
	v_cndmask_b32_e64 v148, 0, v148, s[24:25]
	v_readlane_b32 s24, v250, 23
	v_readlane_b32 s25, v250, 24
	s_nop 1
	v_cndmask_b32_e64 v151, 0, v151, s[24:25]
	s_waitcnt lgkmcnt(0)
	v_fma_f32 v110, v50, v130, 0
	v_fmac_f32_e32 v110, v51, v131
	v_fmac_f32_e32 v110, v52, v129
	v_fmac_f32_e32 v110, v53, v133
	v_fmac_f32_e32 v110, v54, v132
	v_fmac_f32_e32 v110, v55, v135
	v_fmac_f32_e32 v110, v56, v134
	v_fmac_f32_e32 v110, v57, v137
	v_fmac_f32_e32 v110, v58, v136
	v_fmac_f32_e32 v110, v59, v139
	v_fmac_f32_e32 v110, v60, v138
	v_fmac_f32_e32 v110, v61, v141
	v_fmac_f32_e32 v110, v62, v140
	v_fmac_f32_e32 v110, v63, v143
	v_fmac_f32_e32 v110, v64, v142
	v_fmac_f32_e32 v110, v65, v145
	v_fmac_f32_e32 v110, v34, v144
	v_fmac_f32_e32 v110, v35, v147
	v_fmac_f32_e32 v110, v36, v146
	v_fmac_f32_e32 v110, v37, v149
	v_fmac_f32_e32 v110, v38, v148
	v_fmac_f32_e32 v110, v39, v151
	v_fmac_f32_e32 v110, v40, v150
	v_fmac_f32_e32 v110, v41, v153
	v_fmac_f32_e32 v110, v42, v152
	v_fmac_f32_e32 v110, v43, v155
	v_mul_f32_e32 v161, v50, v130
	v_mul_f32_e32 v50, v51, v131
	v_mul_f32_e32 v51, v52, v129
	v_mul_f32_e32 v52, v53, v133
	v_mul_f32_e32 v53, v54, v132
	v_mul_f32_e32 v54, v55, v135
	v_mul_f32_e32 v55, v56, v134
	v_mul_f32_e32 v56, v57, v137
	v_mul_f32_e32 v57, v58, v136
	v_mul_f32_e32 v136, v34, v144
	v_mul_f32_e32 v34, v35, v147
	v_mul_f32_e32 v35, v36, v146
	v_mul_f32_e32 v36, v37, v149
	v_fmac_f32_e32 v110, v44, v154
	v_mul_f32_e32 v129, v59, v139
	v_fmac_f32_e32 v110, v45, v157
	v_cvt_pk_bf16_f32 v59, v51, v52
	v_cvt_pk_bf16_f32 v51, v35, v36
	v_and_b32_e32 v35, 64, v237
	v_fmac_f32_e32 v110, v46, v156
	v_cvt_pk_bf16_f32 v58, v161, v50
	v_cvt_pk_bf16_f32 v50, v136, v34
	v_xor_b32_e32 v34, 32, v237
	v_add_u32_e32 v35, 64, v35
	v_fmac_f32_e32 v110, v47, v159
	v_cmp_lt_i32_e32 vcc, v34, v35
	v_fmac_f32_e32 v110, v48, v158
	v_mul_f32_e32 v37, v38, v148
	v_cndmask_b32_e32 v34, v237, v34, vcc
	v_mul_f32_e32 v38, v39, v151
	v_fmac_f32_e32 v110, v49, v160
	v_lshlrev_b32_e32 v34, 2, v34
	v_mul_f32_e32 v130, v60, v138
	v_mul_f32_e32 v131, v61, v141
	v_mul_f32_e32 v132, v62, v140
	v_mul_f32_e32 v133, v63, v143
	v_mul_f32_e32 v39, v40, v150
	v_mul_f32_e32 v40, v41, v153
	v_mul_f32_e32 v41, v42, v152
	v_mul_f32_e32 v42, v43, v155
	v_cvt_pk_bf16_f32 v62, v57, v129
	v_cvt_pk_bf16_f32 v52, v37, v38
	ds_bpermute_b32 v129, v34, v110
	v_cvt_pk_bf16_f32 v34, v2, v3
	v_cvt_pk_bf16_f32 v35, v4, v5
	v_cvt_pk_bf16_f32 v36, v6, v7
	v_cvt_pk_bf16_f32 v37, v8, v9
	v_mul_f32_e32 v134, v64, v142
	v_cvt_pk_bf16_f32 v60, v53, v54
	v_cvt_pk_bf16_f32 v63, v130, v131
	v_cvt_pk_bf16_f32 v64, v132, v133
	v_cvt_pk_bf16_f32 v53, v39, v40
	v_cvt_pk_bf16_f32 v54, v41, v42
	ds_read2_b64 v[38:41], v126 offset1:2
	ds_read2_b64 v[130:133], v126 offset0:4 offset1:6
	v_mul_f32_e32 v43, v44, v154
	v_mul_f32_e32 v44, v45, v157
	v_mul_f32_e32 v45, v46, v156
	v_mul_f32_e32 v46, v47, v159
	v_mul_f32_e32 v47, v48, v158
	v_mul_f32_e32 v48, v49, v160
	v_cvt_pk_bf16_f32 v61, v55, v56
	v_cvt_pk_bf16_f32 v55, v43, v44
	v_cvt_pk_bf16_f32 v56, v45, v46
	v_cvt_pk_bf16_f32 v57, v47, v48
	s_waitcnt lgkmcnt(1)
	v_mfma_f32_32x32x16_bf16 v[34:49], v[34:37], v[38:41], 0
	v_mul_f32_e32 v135, v65, v145
	v_cvt_pk_bf16_f32 v65, v134, v135
	v_cvt_pk_bf16_f32 v134, v10, v11
	v_cvt_pk_bf16_f32 v135, v12, v13
	v_cvt_pk_bf16_f32 v136, v14, v15
	v_cvt_pk_bf16_f32 v137, v16, v17
	s_waitcnt lgkmcnt(0)
	s_nop 0
	v_mfma_f32_32x32x16_bf16 v[34:49], v[134:137], v[130:133], v[34:49]
	v_cvt_pk_bf16_f32 v130, v18, v19
	v_cvt_pk_bf16_f32 v131, v20, v21
	v_cvt_pk_bf16_f32 v132, v22, v23
	v_cvt_pk_bf16_f32 v133, v24, v25
	ds_read2_b64 v[134:137], v126 offset0:8 offset1:10
	s_waitcnt lgkmcnt(0)
; #define MFMA(a, b, c) __builtin_amdgcn_mfma_f32_32x32x16_bf16((a), (b), (c), 0, 0, 0)
; DI unsigned pk2(float a, float b) { f32x2 v = {a, b}; bf2_t r = __builtin_convertvector(v, bf2_t); return __builtin_bit_cast(unsigned, r); }
; DI float bflo(unsigned v) { return __uint_as_float(v << 16); }
; DI float bfhi(unsigned v) { return __uint_as_float(v & 0xffff0000u); }
; DI void st_bf4(u16* dst, float a, float b, float c, float d) { uint2 u = {pk2(a, b), pk2(c, d)}; *(uint2*)dst = u; }
; DI void mlstm_chain(const Params& p, int layer, char* smem, VBC& vc, int chain) {
;     ...
;                     Z = MFMA(pack8(Cst[dt], sp), ld4x2(qp, qp + 8), Z);
;                 }
; #pragma unroll
;             for (int e = 0; e < 16; ++e) Z[e] *= wit;
; #pragma unroll
;             for (int kk = 0; kk < 4; ++kk) {
;                 const int si = kk >> 1, sp = kk & 1;
;                 Z = MFMA(ld8(sVT + (vh * 32 + r) * AST + si * 32 + sp * 16 + 8 * h), pf[si][sp], Z);
;             }
;             const float den = wit * s_nq[t] + dsum;
;             const float inv = 1.f / fmaxf(fabsf(den), __expf(-mtt));
;             u16* hp = HD + (size_t)(prow0 + t) * 384 + hd * 64 + vh * 32 + 4 * h;
; #pragma unroll
;             for (int g = 0; g < 4; ++g) st_bf4(hp + 8 * g, Z[4 * g] * inv, Z[4 * g + 1] * inv, Z[4 * g + 2] * inv, Z[4 * g + 3] * inv);
;             const float decay = s_sc[0];
;             bf16x8 wv[4];
; #pragma unroll
;             for (int ks = 0; ks < 4; ++ks) {
;                 uint4 vv = *(const uint4*)(sVT + (vh * 32 + r) * AST + ks * 16 + h * 8);
;                 float4 w0 = *(const float4*)(s_w + ks * 16 + 4 * h), w1 = *(const float4*)(s_w + ks * 16 + 8 + 4 * h);
;                 uint4 u;
;                 u.x = pk2(bflo(vv.x) * w0.x, bfhi(vv.x) * w0.y); u.y = pk2(bflo(vv.y) * w0.z, bfhi(vv.y) * w0.w);
;                 u.z = pk2(bflo(vv.z) * w1.x, bfhi(vv.z) * w1.y); u.w = pk2(bflo(vv.w) * w1.z, bfhi(vv.w) * w1.w);
;                 wv[ks] = __builtin_bit_cast(bf16x8, u);
;             }
	v_mfma_f32_32x32x16_bf16 v[34:49], v[130:133], v[134:137], v[34:49]
	v_cvt_pk_bf16_f32 v130, v26, v27
	v_cvt_pk_bf16_f32 v131, v28, v29
	v_cvt_pk_bf16_f32 v132, v30, v31
	v_cvt_pk_bf16_f32 v133, v32, v33
	ds_read2_b64 v[134:137], v126 offset0:12 offset1:14
	s_waitcnt lgkmcnt(0)
	v_mfma_f32_32x32x16_bf16 v[34:49], v[130:133], v[134:137], v[34:49]
	ds_read_b128 v[130:133], v106 offset:27648
	ds_read_b128 v[134:137], v106 offset:27680
	s_nop 9
	v_pk_mul_f32 v[48:49], v[108:109], v[48:49] op_sel_hi:[0,1]
	v_pk_mul_f32 v[46:47], v[108:109], v[46:47] op_sel_hi:[0,1]
	v_pk_mul_f32 v[44:45], v[108:109], v[44:45] op_sel_hi:[0,1]
	v_pk_mul_f32 v[42:43], v[108:109], v[42:43] op_sel_hi:[0,1]
	v_pk_mul_f32 v[40:41], v[108:109], v[40:41] op_sel_hi:[0,1]
	v_pk_mul_f32 v[38:39], v[108:109], v[38:39] op_sel_hi:[0,1]
	v_pk_mul_f32 v[36:37], v[108:109], v[36:37] op_sel_hi:[0,1]
	v_pk_mul_f32 v[34:35], v[108:109], v[34:35] op_sel_hi:[0,1]
	s_waitcnt lgkmcnt(1)
	s_nop 0
	v_mfma_f32_32x32x16_bf16 v[34:49], v[130:133], v[58:61], v[34:49]
	ds_read_b128 v[58:61], v106 offset:27712
	s_waitcnt lgkmcnt(1)
	v_mfma_f32_32x32x16_bf16 v[34:49], v[134:137], v[62:65], v[34:49]
	s_waitcnt lgkmcnt(0)
	v_mfma_f32_32x32x16_bf16 v[34:49], v[58:61], v[50:53], v[34:49]
	ds_read_b128 v[50:53], v106 offset:27744
	s_waitcnt lgkmcnt(0)
	v_mfma_f32_32x32x16_bf16 v[34:49], v[50:53], v[54:57], v[34:49]
	ds_read_b32 v51, v127 offset:38656
	v_add_f32_e32 v50, v110, v129
	s_waitcnt lgkmcnt(0)
	v_fmac_f32_e32 v50, v108, v51
	v_mul_f32_e32 v51, 0xbfb8aa3b, v111
	v_exp_f32_e32 v51, v51
	s_nop 0
	v_max_f32_e64 v50, |v50|, v51
	v_div_scale_f32 v51, s[0:1], v50, v50, 1.0
	v_rcp_f32_e32 v52, v51
	s_movk_i32 s0, 0x300
	v_fma_f32 v53, -v51, v52, 1.0
	v_fmac_f32_e32 v52, v53, v52
	v_div_scale_f32 v53, vcc, 1.0, v50, 1.0
	v_mul_f32_e32 v54, v53, v52
	v_fma_f32 v55, -v51, v54, v53
	v_fmac_f32_e32 v54, v55, v52
	v_fma_f32 v51, -v51, v54, v53
	v_div_fmas_f32 v51, v51, v52, v54
	v_div_fixup_f32 v50, v51, v50, 1.0
	v_add_u32_e32 v51, s62, v122
	v_pk_mul_f32 v[34:35], v[34:35], v[50:51] op_sel_hi:[1,0]
	v_pk_mul_f32 v[36:37], v[36:37], v[50:51] op_sel_hi:[1,0]
	v_mad_i64_i32 v[52:53], s[0:1], v51, s0, v[102:103]
	v_cvt_pk_bf16_f32 v34, v34, v35
	v_cvt_pk_bf16_f32 v35, v36, v37
	global_store_dwordx2 v[52:53], v[34:35], off
	v_pk_mul_f32 v[34:35], v[38:39], v[50:51] op_sel_hi:[1,0]
	v_pk_mul_f32 v[36:37], v[40:41], v[50:51] op_sel_hi:[1,0]
	v_cvt_pk_bf16_f32 v34, v34, v35
	v_cvt_pk_bf16_f32 v35, v36, v37
	global_store_dwordx2 v[52:53], v[34:35], off offset:16
	v_pk_mul_f32 v[34:35], v[42:43], v[50:51] op_sel_hi:[1,0]
	v_pk_mul_f32 v[36:37], v[44:45], v[50:51] op_sel_hi:[1,0]
	v_cvt_pk_bf16_f32 v34, v34, v35
	v_cvt_pk_bf16_f32 v35, v36, v37
	global_store_dwordx2 v[52:53], v[34:35], off offset:32
	v_pk_mul_f32 v[34:35], v[46:47], v[50:51] op_sel_hi:[1,0]
	v_pk_mul_f32 v[36:37], v[48:49], v[50:51] op_sel_hi:[1,0]
	v_cvt_pk_bf16_f32 v34, v34, v35
	v_cvt_pk_bf16_f32 v35, v36, v37
	global_store_dwordx2 v[52:53], v[34:35], off offset:48
	v_mov_b32_e32 v34, s33
	ds_read_b32 v50, v34 offset:39168
	ds_read_b128 v[34:37], v104 offset:38400
	ds_read_b128 v[38:41], v104 offset:38432
	v_lshlrev_b32_e32 v42, 16, v130
	v_and_b32_e32 v43, 0xffff0000, v130
	s_waitcnt lgkmcnt(1)
	v_pk_mul_f32 v[34:35], v[34:35], v[42:43]
	v_lshlrev_b32_e32 v42, 16, v131
	v_and_b32_e32 v43, 0xffff0000, v131
	v_pk_mul_f32 v[36:37], v[36:37], v[42:43]
	v_cvt_pk_bf16_f32 v34, v34, v35
	v_cvt_pk_bf16_f32 v35, v36, v37
	v_lshlrev_b32_e32 v36, 16, v132
	v_and_b32_e32 v37, 0xffff0000, v132
	s_waitcnt lgkmcnt(0)
	v_pk_mul_f32 v[36:37], v[38:39], v[36:37]
	v_lshlrev_b32_e32 v38, 16, v133
	v_and_b32_e32 v39, 0xffff0000, v133
	v_pk_mul_f32 v[38:39], v[40:41], v[38:39]
	v_cvt_pk_bf16_f32 v36, v36, v37
	v_cvt_pk_bf16_f32 v37, v38, v39
	ds_read_b128 v[38:41], v106 offset:27680
	ds_read_b128 v[42:45], v106 offset:27712
	ds_read_b128 v[46:49], v104 offset:38464
	v_pk_mul_f32 v[16:17], v[16:17], v[50:51] op_sel_hi:[1,0]
	v_pk_mul_f32 v[14:15], v[14:15], v[50:51] op_sel_hi:[1,0]
	s_waitcnt lgkmcnt(2)
	v_lshlrev_b32_e32 v52, 16, v38
	v_and_b32_e32 v53, 0xffff0000, v38
	s_waitcnt lgkmcnt(0)
; #define MFMA(a, b, c) __builtin_amdgcn_mfma_f32_32x32x16_bf16((a), (b), (c), 0, 0, 0)
; DI unsigned pk2(float a, float b) { f32x2 v = {a, b}; bf2_t r = __builtin_convertvector(v, bf2_t); return __builtin_bit_cast(unsigned, r); }
; DI float bflo(unsigned v) { return __uint_as_float(v << 16); }
; DI float bfhi(unsigned v) { return __uint_as_float(v & 0xffff0000u); }
; #define VSYNC() vb_sync(vc)
; DI void mlstm_chain(const Params& p, int layer, char* smem, VBC& vc, int chain) {
;     ...
;             const float decay = s_sc[0];
;             bf16x8 wv[4];
; #pragma unroll
;             for (int ks = 0; ks < 4; ++ks) {
;                 uint4 vv = *(const uint4*)(sVT + (vh * 32 + r) * AST + ks * 16 + h * 8);
;                 float4 w0 = *(const float4*)(s_w + ks * 16 + 4 * h), w1 = *(const float4*)(s_w + ks * 16 + 8 + 4 * h);
;                 uint4 u;
;                 u.x = pk2(bflo(vv.x) * w0.x, bfhi(vv.x) * w0.y); u.y = pk2(bflo(vv.y) * w0.z, bfhi(vv.y) * w0.w);
;                 u.z = pk2(bflo(vv.z) * w1.x, bfhi(vv.z) * w1.y); u.w = pk2(bflo(vv.w) * w1.z, bfhi(vv.w) * w1.w);
;                 wv[ks] = __builtin_bit_cast(bf16x8, u);
;             }
; #pragma unroll
;             for (int dt = 0; dt < 2; ++dt)
; #pragma unroll
;                 for (int e = 0; e < 16; ++e) Cst[dt][e] *= decay;
; #pragma unroll
;             for (int ks = 0; ks < 4; ++ks)
; #pragma unroll
;                 for (int dt = 0; dt < 2; ++dt) Cst[dt] = MFMA(ld8(sKT + (dt * 32 + r) * AST + ks * 16 + h * 8), wv[ks], Cst[dt]);
;         }
;         VSYNC();
	v_pk_mul_f32 v[46:47], v[46:47], v[52:53]
	ds_read_b128 v[52:55], v104 offset:38496
	v_lshlrev_b32_e32 v38, 16, v39
	v_and_b32_e32 v39, 0xffff0000, v39
	v_pk_mul_f32 v[38:39], v[48:49], v[38:39]
	v_cvt_pk_bf16_f32 v46, v46, v47
	v_cvt_pk_bf16_f32 v47, v38, v39
	v_lshlrev_b32_e32 v38, 16, v40
	v_and_b32_e32 v39, 0xffff0000, v40
	s_waitcnt lgkmcnt(0)
	v_pk_mul_f32 v[38:39], v[52:53], v[38:39]
	v_lshlrev_b32_e32 v52, 16, v42
	v_cvt_pk_bf16_f32 v48, v38, v39
	v_lshlrev_b32_e32 v38, 16, v41
	v_and_b32_e32 v39, 0xffff0000, v41
	v_pk_mul_f32 v[38:39], v[54:55], v[38:39]
	v_and_b32_e32 v53, 0xffff0000, v42
	v_cvt_pk_bf16_f32 v49, v38, v39
	ds_read_b128 v[38:41], v104 offset:38528
	v_lshlrev_b32_e32 v42, 16, v43
	v_and_b32_e32 v43, 0xffff0000, v43
	v_pk_mul_f32 v[12:13], v[12:13], v[50:51] op_sel_hi:[1,0]
	v_pk_mul_f32 v[10:11], v[10:11], v[50:51] op_sel_hi:[1,0]
	s_waitcnt lgkmcnt(0)
	v_pk_mul_f32 v[38:39], v[38:39], v[52:53]
	v_pk_mul_f32 v[40:41], v[40:41], v[42:43]
	v_cvt_pk_bf16_f32 v38, v38, v39
	v_cvt_pk_bf16_f32 v39, v40, v41
	ds_read_b128 v[40:43], v104 offset:38560
	v_lshlrev_b32_e32 v52, 16, v44
	v_and_b32_e32 v53, 0xffff0000, v44
	v_lshlrev_b32_e32 v44, 16, v45
	v_and_b32_e32 v45, 0xffff0000, v45
	s_waitcnt lgkmcnt(0)
	v_pk_mul_f32 v[40:41], v[40:41], v[52:53]
	v_pk_mul_f32 v[42:43], v[42:43], v[44:45]
	v_cvt_pk_bf16_f32 v40, v40, v41
	v_cvt_pk_bf16_f32 v41, v42, v43
	ds_read_b128 v[42:45], v106 offset:27744
	ds_read_b128 v[52:55], v104 offset:38592
	v_pk_mul_f32 v[8:9], v[8:9], v[50:51] op_sel_hi:[1,0]
	v_pk_mul_f32 v[6:7], v[6:7], v[50:51] op_sel_hi:[1,0]
	v_pk_mul_f32 v[4:5], v[4:5], v[50:51] op_sel_hi:[1,0]
	s_waitcnt lgkmcnt(1)
	v_lshlrev_b32_e32 v56, 16, v42
	v_and_b32_e32 v57, 0xffff0000, v42
	s_waitcnt lgkmcnt(0)
	v_pk_mul_f32 v[52:53], v[52:53], v[56:57]
	v_lshlrev_b32_e32 v56, 16, v44
	v_cvt_pk_bf16_f32 v42, v52, v53
	v_lshlrev_b32_e32 v52, 16, v43
	v_and_b32_e32 v53, 0xffff0000, v43
	v_pk_mul_f32 v[52:53], v[54:55], v[52:53]
	v_and_b32_e32 v57, 0xffff0000, v44
	v_cvt_pk_bf16_f32 v43, v52, v53
	ds_read_b128 v[52:55], v104 offset:38624
	v_pk_mul_f32 v[2:3], v[2:3], v[50:51] op_sel_hi:[1,0]
	v_pk_mul_f32 v[32:33], v[32:33], v[50:51] op_sel_hi:[1,0]
	v_pk_mul_f32 v[30:31], v[30:31], v[50:51] op_sel_hi:[1,0]
	v_pk_mul_f32 v[28:29], v[28:29], v[50:51] op_sel_hi:[1,0]
	s_waitcnt lgkmcnt(0)
	v_pk_mul_f32 v[52:53], v[52:53], v[56:57]
	v_pk_mul_f32 v[26:27], v[26:27], v[50:51] op_sel_hi:[1,0]
	v_cvt_pk_bf16_f32 v44, v52, v53
	v_lshlrev_b32_e32 v52, 16, v45
	v_and_b32_e32 v53, 0xffff0000, v45
	v_pk_mul_f32 v[52:53], v[54:55], v[52:53]
	v_pk_mul_f32 v[24:25], v[24:25], v[50:51] op_sel_hi:[1,0]
	v_cvt_pk_bf16_f32 v45, v52, v53
	v_pk_mul_f32 v[22:23], v[22:23], v[50:51] op_sel_hi:[1,0]
	v_pk_mul_f32 v[20:21], v[20:21], v[50:51] op_sel_hi:[1,0]
	v_pk_mul_f32 v[18:19], v[18:19], v[50:51] op_sel_hi:[1,0]
	ds_read_b128 v[50:53], v107 offset:18432
	ds_read_b128 v[54:57], v107 offset:18464
	s_waitcnt lgkmcnt(1)
	v_mfma_f32_32x32x16_bf16 v[2:17], v[50:53], v[34:37], v[2:17]
	ds_read_b128 v[50:53], v107 offset:23040
	s_waitcnt lgkmcnt(0)
	v_mfma_f32_32x32x16_bf16 v[18:33], v[50:53], v[34:37], v[18:33]
	ds_read_b128 v[34:37], v107 offset:23072
	s_waitcnt lgkmcnt(0)
	v_mfma_f32_32x32x16_bf16 v[18:33], v[34:37], v[46:49], v[18:33]
	ds_read_b128 v[34:37], v107 offset:18496
	v_mfma_f32_32x32x16_bf16 v[2:17], v[54:57], v[46:49], v[2:17]
	s_waitcnt lgkmcnt(0)
	v_mfma_f32_32x32x16_bf16 v[2:17], v[34:37], v[38:41], v[2:17]
	ds_read_b128 v[34:37], v107 offset:23104
	s_waitcnt lgkmcnt(0)
	v_mfma_f32_32x32x16_bf16 v[18:33], v[34:37], v[38:41], v[18:33]
	ds_read_b128 v[34:37], v107 offset:18528
	s_waitcnt lgkmcnt(0)
	v_mfma_f32_32x32x16_bf16 v[2:17], v[34:37], v[42:45], v[2:17]
	ds_read_b128 v[34:37], v107 offset:23136
	s_waitcnt lgkmcnt(0)
	s_waitcnt lgkmcnt(0)
	v_mfma_f32_32x32x16_bf16 v[18:33], v[34:37], v[42:45], v[18:33]
	v_mbcnt_lo_u32_b32 v34, -1, 0
	v_mbcnt_hi_u32_b32 v34, -1, v34
	s_nop 0
	v_cmp_eq_u32_e32 vcc, 0, v34
	s_and_saveexec_b64 s[0:1], vcc
	s_cbranch_execz .LBB0_896
	s_mov_b64 s[24:25], exec
	v_mbcnt_lo_u32_b32 v34, s24, 0
	v_mbcnt_hi_u32_b32 v34, s25, v34
	v_cmp_eq_u32_e32 vcc, 0, v34
	s_and_b64 s[26:27], exec, vcc
	s_mov_b64 exec, s[26:27]
	s_bcnt1_i32_b64 s24, s[24:25]
	v_mov_b32_e32 v34, s35
	v_mov_b32_e32 v35, s24
	ds_add_u32 v34, v35

; DI int lane_id() { int l; asm volatile("v_mbcnt_lo_u32_b32 %0, -1, 0\n\tv_mbcnt_hi_u32_b32 %0, -1, %0" : "=v"(l)); return l; }
; DI void vb_sync(VBC& vc) {
;     vc.gen += 4u;
;     __builtin_amdgcn_fence(__ATOMIC_RELEASE, "workgroup");
;     asm volatile("s_waitcnt lgkmcnt(0)" ::: "memory");
;     if (lane_id() == 0) __hip_atomic_fetch_add(vc.cnt, 1u, __ATOMIC_RELAXED, __HIP_MEMORY_SCOPE_WORKGROUP);
;     while (__hip_atomic_load(vc.cnt, __ATOMIC_RELAXED, __HIP_MEMORY_SCOPE_WORKGROUP) < vc.gen) __builtin_amdgcn_s_sleep(1);
;     __builtin_amdgcn_fence(__ATOMIC_ACQUIRE, "workgroup");
; }
.LBB0_897:
	v_mov_b32_e32 v34, s35
	s_sleep 1
	ds_read_b32 v34, v34
	s_waitcnt lgkmcnt(0)
	v_cmp_gt_u32_e32 vcc, s60, v34
	s_cbranch_vccnz .LBB0_897
	s_branch .LBB0_756
.LBB0_902:
	s_addk_i32 s56, 0x330
	s_setprio 0

; #define VSYNC() vb_sync(vc)
; template <int NS>
; DI void attn_item(const Params& p, int layer, char* smem, VBC& vc, int b, int hq, int qblk) {
;     ...
;     auto tile_ptrs = [&](int it, const u16*& kp, const u16*& vp) {
;         if (it < lat1 - lat0) { int kt = lat0 + it; kp = P + (size_t)(b * SEQ + kt * 64) * PC + kcol; vp = VT + kt * 64; }
;         else { int c = it - (lat1 - lat0); kp = P + (size_t)(NLAT + b * CTXL + c * 64) * PC + kcol; vp = VT + SEQ + c * 64; }
;     };
;     auto dma_tile = [&](int it, int st) {
;         const u16 *kp, *vp; tile_ptrs(it, kp, vp);
; #pragma unroll
;         for (int i = 0; i < 2; ++i) {
;             const int row = wave4 * 16 + i * 8 + drow;
;             const int chunk = dslot ^ ((row >> 1) & 7);
;             lds_u32* dk = (lds_u32*)(sK + st * 8192 + (wave4 * 16 + i * 8) * 64);
;             lds_u32* dv = (lds_u32*)(sK + st * 8192 + 4096 + (wave4 * 16 + i * 8) * 64);
;             __builtin_amdgcn_global_load_lds((const unsigned*)(kp + (size_t)row * PC + chunk * 8), dk, 16, 0, 0);
;             __builtin_amdgcn_global_load_lds((const unsigned*)(vp + (size_t)row * KVS + chunk * 8), dv, 16, 0, 0);
;         }
;     };
;     const int hs16 = ((h ^ ((r >> 1) & 7)) << 3);
;     const bf16x8 kones = __builtin_bit_cast(bf16x8, (uint4){0x00003F80u, 0u, 0u, 0u});
;     auto run_tiles = [&](const bool fast) {
;     dma_tile(0, 0);
;     asm volatile("s_waitcnt vmcnt(0)" ::: "memory");
;     VSYNC();
;     for (int it = 0; it < ntiles; ++it) {
;         const int buf = it & 1;
;         if (it + 1 < ntiles) dma_tile(it + 1, buf ^ 1);
;         const u16* cK = sK + buf * 8192; const u16* cV = cK + 4096;
;         const bool is_lat = it < lat1 - lat0;
;         const int kpos0 = (lat0 + it) * 64;
.Lr_iter0:
	s_and_b64 vcc, exec, s[14:15]
	s_cbranch_vccz .Lorig_945B
	v_readlane_b32 s0, v252, 21
	s_lshr_b32 s0, s0, 4
	s_add_i32 s0, s0, s33
	s_add_i32 s0, s0, 0x10000
	v_mov_b32_e32 v2, s0
	v_mov_b32_e32 v3, 0
	s_mov_b64 exec, 1
	ds_write_b32 v2, v3
	s_mov_b64 exec, -1
	s_branch .Lorig_945B
.Lr_takeover:
	s_mov_b32 s47, 3
	s_mov_b32 s55, 0x8000
	s_cmp_lt_u32 s47, s21
	s_cselect_b64 s[0:1], -1, 0
	s_sub_i32 s17, s47, s21
	s_min_u32 s17, s47, s17
	s_and_b64 s[0:1], s[0:1], exec
	s_cselect_b32 s0, s20, s27
	s_cselect_b32 s1, s25, s41
	s_cselect_b32 s48, s24, s40
	s_lshl_b32 s49, s17, 6
	s_add_i32 s49, s49, s0
	s_lshl_b32 s0, s17, 7
	s_add_u32 s0, s48, s0
	s_addc_u32 s1, s1, 0
	s_mul_hi_i32 s17, s49, 0x1a80
	s_mulk_i32 s49, 0x1a80
	s_add_u32 s48, s42, s49
	s_addc_u32 s49, s43, s17
	s_add_i32 s17, s33, s55
	v_lshl_add_u32 v5, v241, 1, s17
	v_lshl_add_u64 v[2:3], s[48:49], 0, v[206:207]
	v_mov_b32_e32 v223, v1
	v_readfirstlane_b32 s54, v5
	v_add_u32_e32 v6, 0x2000, v5
	v_lshl_add_u64 v[2:3], v[2:3], 0, v[222:223]
	s_mov_b32 m0, s54
	v_readfirstlane_b32 s54, v6
	global_load_lds_dwordx4 v[2:3], off
	v_lshl_add_u64 v[2:3], s[0:1], 0, v[208:209]
	v_lshl_add_u64 v[2:3], v[2:3], 0, v[222:223]
	s_mov_b32 m0, s54
	v_lshl_add_u32 v5, v243, 1, s17
	global_load_lds_dwordx4 v[2:3], off
	v_lshl_add_u64 v[2:3], s[48:49], 0, v[210:211]
	v_mov_b32_e32 v225, v1
	v_readfirstlane_b32 s17, v5
	v_add_u32_e32 v6, 0x2000, v5
	v_lshl_add_u64 v[2:3], v[2:3], 0, v[224:225]
	s_mov_b32 m0, s17
	s_nop 0
	global_load_lds_dwordx4 v[2:3], off
	v_lshl_add_u64 v[2:3], s[0:1], 0, v[212:213]
	v_readfirstlane_b32 s0, v6
	v_lshl_add_u64 v[2:3], v[2:3], 0, v[224:225]
	s_mov_b32 m0, s0
	s_nop 0
	global_load_lds_dwordx4 v[2:3], off
	s_movk_i32 s17, 0x2000
	s_branch .Lr_body
.Lr_loop:
	s_waitcnt vmcnt(0)
	v_readlane_b32 s0, v252, 21
	s_lshr_b32 s0, s0, 4
	s_add_i32 s0, s0, s33
	s_add_i32 s0, s0, 0x10000
	s_add_i32 s1, s46, -1
	v_mov_b32_e32 v2, s0
	v_mov_b32_e32 v3, s1
	s_mov_b64 exec, 1
	ds_write_b32 v2, v3
	s_mov_b64 exec, -1
	s_add_i32 s1, s46, -2
	s_max_i32 s1, s1, 1
	s_add_i32 s0, s33, 0x10000
	v_mov_b32_e32 v6, s0
.Lr_poll:
	ds_read_b128 v[8:11], v6
	s_waitcnt lgkmcnt(0)
	v_min3_u32 v8, v8, v9, v10
	v_min_u32_e32 v8, v8, v11
	v_cmp_gt_u32_e32 vcc, s1, v8
	s_cbranch_vccz .Lr_go
	s_sleep 1
	s_branch .Lr_poll
.Lr_go:
	s_add_i32 s47, s46, 2
	s_cmp_lt_u32 s47, s26
	s_cbranch_scc0 .Lr_nodma
	s_add_i32 s0, s46, 1
	s_and_b32 s0, s0, 3
	s_not_b32 s1, s0
	s_lshr_b32 s1, s1, 1
	s_and_b32 s1, s1, 1
	s_xor_b32 s0, s0, s1
	s_lshl_b32 s55, s0, 14
	s_cmp_lt_u32 s47, s21
	s_cselect_b64 s[0:1], -1, 0
	s_sub_i32 s17, s47, s21
	s_min_u32 s17, s47, s17
	s_and_b64 s[0:1], s[0:1], exec
	s_cselect_b32 s0, s20, s27
	s_cselect_b32 s1, s25, s41
	s_cselect_b32 s48, s24, s40
	s_lshl_b32 s49, s17, 6
	s_add_i32 s49, s49, s0
	s_lshl_b32 s0, s17, 7
	s_add_u32 s0, s48, s0
	s_addc_u32 s1, s1, 0
	s_mul_hi_i32 s17, s49, 0x1a80
	s_mulk_i32 s49, 0x1a80
	s_add_u32 s48, s42, s49
	s_addc_u32 s49, s43, s17
	s_add_i32 s17, s33, s55
	v_lshl_add_u32 v5, v241, 1, s17
	v_lshl_add_u64 v[2:3], s[48:49], 0, v[206:207]
	v_mov_b32_e32 v223, v1
	v_readfirstlane_b32 s54, v5
	v_add_u32_e32 v6, 0x2000, v5
	v_lshl_add_u64 v[2:3], v[2:3], 0, v[222:223]
	s_mov_b32 m0, s54
	v_readfirstlane_b32 s54, v6
	global_load_lds_dwordx4 v[2:3], off
	v_lshl_add_u64 v[2:3], s[0:1], 0, v[208:209]
	v_lshl_add_u64 v[2:3], v[2:3], 0, v[222:223]
	s_mov_b32 m0, s54
	v_lshl_add_u32 v5, v243, 1, s17
	global_load_lds_dwordx4 v[2:3], off
	v_lshl_add_u64 v[2:3], s[48:49], 0, v[210:211]
	v_mov_b32_e32 v225, v1
	v_readfirstlane_b32 s17, v5
	v_add_u32_e32 v6, 0x2000, v5
	v_lshl_add_u64 v[2:3], v[2:3], 0, v[224:225]
	s_mov_b32 m0, s17
	s_nop 0
	global_load_lds_dwordx4 v[2:3], off
	v_lshl_add_u64 v[2:3], s[0:1], 0, v[212:213]
	v_readfirstlane_b32 s0, v6
	v_lshl_add_u64 v[2:3], v[2:3], 0, v[224:225]
	s_mov_b32 m0, s0
	s_nop 0
	global_load_lds_dwordx4 v[2:3], off
.Lr_nodma:
	s_add_i32 s0, s46, -1
	s_and_b32 s0, s0, 3
	s_not_b32 s1, s0
	s_lshr_b32 s1, s1, 1
	s_and_b32 s1, s1, 1
	s_xor_b32 s0, s0, s1
	s_lshl_b32 s17, s0, 13
.Lr_body:
	s_setprio 1
	v_lshl_add_u32 v226, s17, 1, v248
	v_lshl_add_u32 v5, v201, 1, v226
	v_lshl_add_u32 v6, v245, 1, v226
	ds_read_b128 v[112:115], v5
	ds_read_b128 v[116:119], v5 offset:4096
	v_lshl_add_u32 v223, v246, 1, v226
	ds_read_b128 v[120:123], v6
	ds_read_b128 v[124:127], v6 offset:4096
	v_lshl_add_u32 v225, v247, 1, v226
	ds_read_b128 v[128:131], v223
	ds_read_b128 v[132:135], v223 offset:4096
	ds_read_b128 v[136:139], v225
	ds_read_b128 v[140:143], v225 offset:4096
	v_mov_b32_e32 v2, 0
	v_mov_b32_e32 v3, 0
	v_mov_b32_e32 v12, s52
	v_mov_b32_e32 v13, 0
	v_mov_b32_e32 v14, 0
	v_mov_b32_e32 v15, 0
	v_mov_b32_e32 v8, v192
	v_mov_b32_e32 v9, 0
	v_mov_b32_e32 v10, 0
	v_mov_b32_e32 v11, 0
	s_waitcnt lgkmcnt(7)
	v_mfma_f32_32x32x16_bf16 v[96:111], v[112:115], v[176:179], 0
	s_waitcnt lgkmcnt(6)
	v_mfma_f32_32x32x16_bf16 v[80:95], v[116:119], v[176:179], 0
	s_waitcnt lgkmcnt(5)
	v_mfma_f32_32x32x16_bf16 v[96:111], v[120:123], v[180:183], v[96:111]
	s_waitcnt lgkmcnt(4)
	v_mfma_f32_32x32x16_bf16 v[80:95], v[124:127], v[180:183], v[80:95]
	ds_read_b128 v[112:115], v5 offset:8192
	ds_read_b128 v[116:119], v5 offset:12288
	v_mfma_f32_32x32x16_bf16 v[96:111], v[12:15], v[0:3], v[96:111]
	ds_read_b128 v[120:123], v6 offset:8192
	ds_read_b128 v[124:127], v6 offset:12288
	v_mfma_f32_32x32x16_bf16 v[80:95], v[12:15], v[0:3], v[80:95]
	s_waitcnt lgkmcnt(7)
	v_mfma_f32_32x32x16_bf16 v[144:159], v[128:131], v[184:187], 0
	s_waitcnt lgkmcnt(6)
	v_mfma_f32_32x32x16_bf16 v[160:175], v[132:135], v[184:187], 0
	s_waitcnt lgkmcnt(5)
; #define MFMA(a, b, c) __builtin_amdgcn_mfma_f32_32x32x16_bf16((a), (b), (c), 0, 0, 0)
; template <int NS>
; DI void attn_item(const Params& p, int layer, char* smem, VBC& vc, int b, int hq, int qblk) {
;     ...
;             if (fixed) {
;                 float ls = 0.f;
; #pragma unroll
;                 for (int kt2 = 0; kt2 < 2; ++kt2)
; #pragma unroll
;                     for (int e = 0; e < 16; ++e) { const float pv = __builtin_amdgcn_exp2f(s[kt2][e]); s[kt2][e] = pv; ls += pv; }
;                 lrun[m] += ls;
;     ...
;             for (int kt2 = 0; kt2 < 2; ++kt2) { pf[kt2][0] = pack8(s[kt2], 0); pf[kt2][1] = pack8(s[kt2], 1); }
;         };
;         auto pvm = [&](const int m, const bf16x8 (&pf)[2][2]) {
;             __builtin_amdgcn_s_setprio(1);
; #pragma unroll
;             for (int kk = 0; kk < 4; ++kk)
; #pragma unroll
;                 for (int dvt = 0; dvt < 2; ++dvt) O[m][dvt] = MFMA(ld8(cV + (dvt * 32 + r) * 64 + ((kk * 16) ^ hs16)), pf[kk >> 1][kk & 1], O[m][dvt]);
;             __builtin_amdgcn_s_setprio(0);
;         };
	v_mfma_f32_32x32x16_bf16 v[144:159], v[136:139], v[188:191], v[144:159]
	s_waitcnt lgkmcnt(4)
	v_mfma_f32_32x32x16_bf16 v[160:175], v[140:143], v[188:191], v[160:175]
	ds_read_b128 v[128:131], v223 offset:8192
	ds_read_b128 v[132:135], v223 offset:12288
	v_exp_f32_e32 v96, v96
	v_exp_f32_e32 v97, v97
	v_exp_f32_e32 v98, v98
	v_exp_f32_e32 v99, v99
	v_mfma_f32_32x32x16_bf16 v[144:159], v[12:15], v[8:11], v[144:159]
	ds_read_b128 v[136:139], v225 offset:8192
	ds_read_b128 v[140:143], v225 offset:12288
	v_exp_f32_e32 v100, v100
	v_exp_f32_e32 v101, v101
	v_pk_add_f32 v[2:3], v[96:97], v[98:99]
	v_exp_f32_e32 v102, v102
	v_exp_f32_e32 v103, v103
	v_pk_add_f32 v[2:3], v[2:3], v[100:101]
	v_mfma_f32_32x32x16_bf16 v[160:175], v[12:15], v[8:11], v[160:175]
	v_exp_f32_e32 v104, v104
	v_exp_f32_e32 v105, v105
	v_pk_add_f32 v[2:3], v[2:3], v[102:103]
	v_exp_f32_e32 v106, v106
	v_exp_f32_e32 v107, v107
	v_pk_add_f32 v[2:3], v[2:3], v[104:105]
	v_exp_f32_e32 v108, v108
	v_exp_f32_e32 v109, v109
	v_pk_add_f32 v[2:3], v[2:3], v[106:107]
	v_exp_f32_e32 v110, v110
	v_exp_f32_e32 v111, v111
	v_pk_add_f32 v[2:3], v[2:3], v[108:109]
	v_exp_f32_e32 v80, v80
	v_exp_f32_e32 v81, v81
	v_pk_add_f32 v[2:3], v[2:3], v[110:111]
	v_exp_f32_e32 v82, v82
	v_exp_f32_e32 v83, v83
	v_pk_add_f32 v[2:3], v[2:3], v[80:81]
	v_exp_f32_e32 v84, v84
	v_exp_f32_e32 v85, v85
	v_pk_add_f32 v[2:3], v[2:3], v[82:83]
	v_exp_f32_e32 v86, v86
	v_exp_f32_e32 v87, v87
	v_pk_add_f32 v[2:3], v[2:3], v[84:85]
	v_exp_f32_e32 v88, v88
	v_exp_f32_e32 v89, v89
	v_pk_add_f32 v[2:3], v[2:3], v[86:87]
	v_exp_f32_e32 v90, v90
	v_exp_f32_e32 v91, v91
	v_pk_add_f32 v[2:3], v[2:3], v[88:89]
	v_exp_f32_e32 v92, v92
	v_exp_f32_e32 v93, v93
	v_pk_add_f32 v[2:3], v[2:3], v[90:91]
	v_exp_f32_e32 v94, v94
	v_exp_f32_e32 v95, v95
	v_pk_add_f32 v[2:3], v[2:3], v[92:93]
	v_mov_b32_e32 v96, v96
	v_pk_add_f32 v[2:3], v[2:3], v[94:95]
	s_setprio 0
	v_cvt_pk_bf16_f32 v96, v96, v97
	v_cvt_pk_bf16_f32 v97, v98, v99
	v_cvt_pk_bf16_f32 v98, v100, v101
	v_cvt_pk_bf16_f32 v99, v102, v103
	v_cvt_pk_bf16_f32 v100, v104, v105
	v_cvt_pk_bf16_f32 v101, v106, v107
	v_cvt_pk_bf16_f32 v102, v108, v109
	v_cvt_pk_bf16_f32 v103, v110, v111
	v_cvt_pk_bf16_f32 v80, v80, v81
	v_cvt_pk_bf16_f32 v81, v82, v83
	v_cvt_pk_bf16_f32 v82, v84, v85
	v_cvt_pk_bf16_f32 v83, v86, v87
	v_cvt_pk_bf16_f32 v84, v88, v89
	v_cvt_pk_bf16_f32 v85, v90, v91
	v_cvt_pk_bf16_f32 v86, v92, v93
	v_cvt_pk_bf16_f32 v87, v94, v95
	v_add_f32_e32 v2, v2, v3
	v_add_f32_e32 v194, v194, v2
	s_setprio 1
	s_waitcnt lgkmcnt(7)
	v_mfma_f32_32x32x16_bf16 v[64:79], v[112:115], v[96:99], v[64:79]
	v_exp_f32_e32 v144, v144
	v_exp_f32_e32 v145, v145
	v_exp_f32_e32 v146, v146
	v_exp_f32_e32 v147, v147
	v_exp_f32_e32 v148, v148
	v_exp_f32_e32 v149, v149
	v_pk_add_f32 v[14:15], v[144:145], v[146:147]
	v_exp_f32_e32 v150, v150
	s_waitcnt lgkmcnt(6)
	v_mfma_f32_32x32x16_bf16 v[32:47], v[116:119], v[96:99], v[32:47]
	v_exp_f32_e32 v151, v151
	v_pk_add_f32 v[14:15], v[14:15], v[148:149]
	v_exp_f32_e32 v152, v152
	v_exp_f32_e32 v153, v153
	v_pk_add_f32 v[14:15], v[14:15], v[150:151]
	v_exp_f32_e32 v154, v154
	v_exp_f32_e32 v155, v155
	v_pk_add_f32 v[14:15], v[14:15], v[152:153]
	s_waitcnt lgkmcnt(5)
	v_mfma_f32_32x32x16_bf16 v[64:79], v[120:123], v[100:103], v[64:79]
	v_exp_f32_e32 v156, v156
	v_exp_f32_e32 v157, v157
	v_pk_add_f32 v[14:15], v[14:15], v[154:155]
	v_exp_f32_e32 v158, v158
	v_exp_f32_e32 v159, v159
	v_pk_add_f32 v[14:15], v[14:15], v[156:157]
	v_exp_f32_e32 v160, v160
	v_exp_f32_e32 v161, v161
	s_waitcnt lgkmcnt(4)
	v_mfma_f32_32x32x16_bf16 v[32:47], v[124:127], v[100:103], v[32:47]
	v_pk_add_f32 v[14:15], v[14:15], v[158:159]
	v_exp_f32_e32 v162, v162
	v_exp_f32_e32 v163, v163
	v_pk_add_f32 v[14:15], v[14:15], v[160:161]
	v_exp_f32_e32 v164, v164
	v_exp_f32_e32 v165, v165
	v_pk_add_f32 v[14:15], v[14:15], v[162:163]
	v_exp_f32_e32 v166, v166
	s_waitcnt lgkmcnt(3)
	v_mfma_f32_32x32x16_bf16 v[64:79], v[128:131], v[80:83], v[64:79]
	v_exp_f32_e32 v167, v167
	v_pk_add_f32 v[14:15], v[14:15], v[164:165]
	v_exp_f32_e32 v168, v168
	v_exp_f32_e32 v169, v169
	v_pk_add_f32 v[14:15], v[14:15], v[166:167]
	v_exp_f32_e32 v170, v170
	v_exp_f32_e32 v171, v171
	v_pk_add_f32 v[14:15], v[14:15], v[168:169]
	s_waitcnt lgkmcnt(2)
	v_mfma_f32_32x32x16_bf16 v[32:47], v[132:135], v[80:83], v[32:47]
	v_exp_f32_e32 v172, v172
	v_exp_f32_e32 v173, v173
	v_pk_add_f32 v[14:15], v[14:15], v[170:171]
	v_exp_f32_e32 v174, v174
	v_exp_f32_e32 v175, v175
	v_pk_add_f32 v[14:15], v[14:15], v[172:173]
	v_mov_b32_e32 v144, v144
	v_pk_add_f32 v[14:15], v[14:15], v[174:175]
	s_waitcnt lgkmcnt(1)
	v_mfma_f32_32x32x16_bf16 v[64:79], v[136:139], v[84:87], v[64:79]
	s_waitcnt lgkmcnt(0)
	v_mfma_f32_32x32x16_bf16 v[32:47], v[140:143], v[84:87], v[32:47]
	s_setprio 0
	v_cvt_pk_bf16_f32 v144, v144, v145
	v_cvt_pk_bf16_f32 v145, v146, v147
	v_cvt_pk_bf16_f32 v146, v148, v149
	v_cvt_pk_bf16_f32 v147, v150, v151
	v_cvt_pk_bf16_f32 v148, v152, v153
	v_cvt_pk_bf16_f32 v149, v154, v155
	v_cvt_pk_bf16_f32 v150, v156, v157
	v_cvt_pk_bf16_f32 v151, v158, v159
	v_cvt_pk_bf16_f32 v160, v160, v161
	v_cvt_pk_bf16_f32 v161, v162, v163
	v_cvt_pk_bf16_f32 v162, v164, v165
	v_cvt_pk_bf16_f32 v163, v166, v167
	v_cvt_pk_bf16_f32 v164, v168, v169
	v_cvt_pk_bf16_f32 v165, v170, v171
	v_cvt_pk_bf16_f32 v166, v172, v173
	v_cvt_pk_bf16_f32 v167, v174, v175
	v_add_f32_e32 v193, v14, v15
	v_add_f32_e32 v4, v4, v193
	s_nop 1
	s_setprio 1
	v_mfma_f32_32x32x16_bf16 v[48:63], v[112:115], v[144:147], v[48:63]
	v_mfma_f32_32x32x16_bf16 v[16:31], v[116:119], v[144:147], v[16:31]
	v_mfma_f32_32x32x16_bf16 v[48:63], v[120:123], v[148:151], v[48:63]
	v_mfma_f32_32x32x16_bf16 v[16:31], v[124:127], v[148:151], v[16:31]
	v_mfma_f32_32x32x16_bf16 v[48:63], v[128:131], v[160:163], v[48:63]
	v_mfma_f32_32x32x16_bf16 v[16:31], v[132:135], v[160:163], v[16:31]
	v_mfma_f32_32x32x16_bf16 v[48:63], v[136:139], v[164:167], v[48:63]
	v_mfma_f32_32x32x16_bf16 v[16:31], v[140:143], v[164:167], v[16:31]
	s_setprio 0
	s_cmp_lg_u32 s46, s44
	s_cbranch_scc0 .Lr_exit
	s_add_i32 s46, s46, 1
	s_branch .Lr_loop
.Lr_exit:
	v_mov_b32_e32 v223, v194
	v_mov_b32_e32 v193, v4
	v_mov_b32_e32 v226, v7
	v_mov_b32_e32 v3, v0
	v_mov_b32_e32 v0, v249
	v_mov_b32_e32 v195, v192
	s_waitcnt vmcnt(0)
	s_add_i32 s45, s45, -4
	s_branch .LBB0_964
